# non-temporal (nt) hint on the f32 Y stores of the final-layer P8 ple-gate epilogue (streaming output, never re-read)
# speedup vs baseline: 1.0058x; 1.0058x over previous
.LBB0_1519:
	s_mov_b64 s[6:7], s[54:55]
	s_add_u32 s24, s6, 0x1a0d2000
	s_addc_u32 s25, s7, 0
	s_lshl_b32 s20, s20, 8
	s_lshl_b32 s11, s11, 6
	s_add_i32 s26, s11, s20
	v_or_b32_e32 v130, s26, v179
	v_mov_b32_e32 v175, v1
	v_lshl_add_u64 v[132:133], s[6:7], 0, v[174:175]
	s_mov_b64 s[6:7], 0xaa88000
	v_ashrrev_i32_e32 v131, 31, v130
	v_lshl_add_u64 v[132:133], v[132:133], 0, s[6:7]
	v_lshlrev_b64 v[134:135], 6, v[130:131]
	v_or_b32_e32 v136, 16, v130
	s_mov_b64 s[22:23], s[52:53]
	v_lshl_add_u64 v[134:135], v[132:133], 0, v[134:135]
	v_ashrrev_i32_e32 v137, 31, v136
	global_load_dwordx4 v[158:161], v[134:135], off
	v_lshlrev_b64 v[136:137], 6, v[136:137]
	v_lshl_add_u64 v[136:137], v[132:133], 0, v[136:137]
	global_load_dwordx4 v[170:173], v[136:137], off
	s_lshl_b32 s6, s18, 8
	s_lshl_b32 s7, s9, 5
	v_or_b32_e32 v131, s11, v179
	s_or_b32 s6, s7, s6
	v_add_u32_e32 v186, s20, v131
	v_lshl_or_b32 v184, v181, 3, s6
	v_ashrrev_i32_e32 v187, 31, v186
	v_ashrrev_i32_e32 v185, 31, v184
	v_lshlrev_b64 v[138:139], 10, v[186:187]
	v_lshl_add_u64 v[138:139], v[138:139], 0, v[184:185]
	v_lshlrev_b64 v[154:155], 1, v[138:139]
	v_lshl_add_u64 v[140:141], s[24:25], 0, v[154:155]
	global_load_dwordx4 v[192:195], v[140:141], off
	v_lshl_add_u64 v[156:157], v[138:139], 2, s[22:23]
	global_load_dwordx4 v[198:201], v[156:157], off offset:16
	global_load_dwordx4 v[202:205], v[156:157], off
	v_or_b32_e32 v136, 32, v130
	v_or_b32_e32 v130, 48, v130
	v_or_b32_e32 v190, 16, v186
	v_ashrrev_i32_e32 v137, 31, v136
	v_ashrrev_i32_e32 v131, 31, v130
	v_ashrrev_i32_e32 v191, 31, v190
	v_lshlrev_b64 v[136:137], 6, v[136:137]
	v_lshlrev_b64 v[130:131], 6, v[130:131]
	v_lshlrev_b64 v[140:141], 10, v[190:191]
	v_lshl_add_u64 v[136:137], v[132:133], 0, v[136:137]
	v_lshl_add_u64 v[130:131], v[132:133], 0, v[130:131]
	v_add_co_u32_e32 v132, vcc, s84, v134
	v_lshl_add_u64 v[162:163], v[140:141], 0, v[184:185]
	v_or_b32_e32 v154, 0x100, v154
	v_lshlrev_b64 v[138:139], 12, v[186:187]
	v_addc_co_u32_e32 v133, vcc, 0, v135, vcc
	v_lshl_add_u64 v[164:165], v[162:163], 2, s[22:23]
	v_lshl_add_u64 v[214:215], s[24:25], 0, v[154:155]
	v_lshl_add_u64 v[218:219], s[22:23], 0, v[138:139]
	global_load_dwordx4 v[150:153], v[136:137], off
	global_load_dwordx4 v[146:149], v[130:131], off
	global_load_dwordx4 v[142:145], v[132:133], off
	global_load_dwordx4 v[138:141], v[132:133], off offset:1024
	s_nop 0
	global_load_dwordx4 v[134:137], v[132:133], off offset:2048
	s_nop 0
	global_load_dwordx4 v[130:133], v[132:133], off offset:3072
	s_nop 0
	global_load_dwordx4 v[206:209], v[156:157], off offset:528
	global_load_dwordx4 v[210:213], v[156:157], off offset:512
	v_lshlrev_b64 v[188:189], 1, v[162:163]
	global_load_dwordx4 v[166:169], v[164:165], off offset:16
	global_load_dwordx4 v[174:177], v[164:165], off
	global_load_dwordx4 v[154:157], v[164:165], off offset:528
	s_nop 0
	global_load_dwordx4 v[162:165], v[164:165], off offset:512
	v_lshl_add_u64 v[220:221], s[24:25], 0, v[188:189]
	global_load_dwordx4 v[214:217], v[214:215], off
	v_or_b32_e32 v188, 0x100, v188
	v_lshl_add_u64 v[188:189], s[24:25], 0, v[188:189]
	s_waitcnt vmcnt(0)
	v_mov_b32_e32 v222, v159
	v_mov_b32_e32 v223, v160
	v_mov_b32_e32 v159, v161
	v_pk_add_f32 v[158:159], v[222:223], v[158:159]
	v_mov_b32_e32 v160, v171
	v_mov_b32_e32 v161, v172
	v_mov_b32_e32 v171, v173
	v_add_f32_e32 v179, v158, v159
	v_pk_add_f32 v[158:159], v[160:161], v[170:171]
	ds_swizzle_b32 v181, v179 offset:swizzle(SWAP,16)
	v_add_f32_e32 v183, v158, v159
	global_load_dwordx4 v[170:173], v[220:221], off
	global_load_dwordx4 v[158:161], v[188:189], off
	ds_swizzle_b32 v187, v183 offset:swizzle(SWAP,16)
	s_waitcnt lgkmcnt(1)
	v_add_f32_e32 v179, v179, v181
	v_mov_b32_e32 v181, v179
	s_nop 1
	v_permlane32_swap_b32_e32 v179, v181
	v_add_f32_e32 v179, v179, v181
	v_fmamk_f32 v179, v179, 0x3a800000, v254
	v_rsq_f32_e32 v220, v179
	s_waitcnt lgkmcnt(0)
	v_add_f32_e32 v183, v183, v187
	v_mov_b32_e32 v187, v183
	s_nop 1
	v_permlane32_swap_b32_e32 v183, v187
	v_pk_mul_f32 v[126:127], v[126:127], v[220:221] op_sel_hi:[1,0]
	v_pk_mul_f32 v[222:223], v[124:125], v[220:221] op_sel_hi:[1,0]
	v_mul_f32_e32 v124, 0xbfb8aa3b, v126
	v_mul_f32_e32 v125, 0xbfb8aa3b, v127
	v_exp_f32_e32 v124, v124
	v_exp_f32_e32 v125, v125
	v_pk_mul_f32 v[128:129], v[128:129], v[220:221] op_sel_hi:[1,0]
	v_lshlrev_b32_e32 v126, 16, v192
	v_add_f32_e32 v124, 1.0, v124
	v_add_f32_e32 v125, 1.0, v125
	v_mul_f32_e32 v128, 0xbfb8aa3b, v128
	v_mul_f32_e32 v129, 0xbfb8aa3b, v129
	v_rcp_f32_e32 v124, v124
	v_rcp_f32_e32 v125, v125
	v_exp_f32_e32 v128, v128
	v_exp_f32_e32 v129, v129
	v_and_b32_e32 v127, 0xffff0000, v192
	v_pk_fma_f32 v[124:125], v[124:125], v[126:127], v[202:203]
	v_add_f32_e32 v126, 1.0, v128
	v_add_f32_e32 v127, 1.0, v129
	v_rcp_f32_e32 v126, v126
	v_rcp_f32_e32 v127, v127
	v_add_f32_e32 v179, v183, v187
	v_pk_mul_f32 v[122:123], v[122:123], v[220:221] op_sel_hi:[1,0]
	v_lshlrev_b32_e32 v128, 16, v193
	v_and_b32_e32 v129, 0xffff0000, v193
	v_fmamk_f32 v179, v179, 0x3a800000, v254
	v_mul_f32_e32 v122, 0xbfb8aa3b, v122
	v_mul_f32_e32 v123, 0xbfb8aa3b, v123
	v_pk_fma_f32 v[126:127], v[126:127], v[128:129], v[204:205]
	v_mul_f32_e32 v129, 0xbfb8aa3b, v222
	v_rsq_f32_e32 v188, v179
	v_exp_f32_e32 v122, v122
	v_exp_f32_e32 v123, v123
	v_exp_f32_e32 v179, v129
	v_mul_f32_e32 v129, 0xbfb8aa3b, v223
	v_exp_f32_e32 v181, v129
	v_add_f32_e32 v122, 1.0, v122
	v_add_f32_e32 v123, 1.0, v123
	v_add_f32_e32 v179, 1.0, v179
	v_rcp_f32_e32 v122, v122
	v_rcp_f32_e32 v123, v123
	v_rcp_f32_e32 v202, v179
	v_add_f32_e32 v179, 1.0, v181
	v_rcp_f32_e32 v203, v179
	v_lshlrev_b32_e32 v128, 16, v194
	v_and_b32_e32 v129, 0xffff0000, v194
	v_pk_fma_f32 v[192:193], v[122:123], v[128:129], v[198:199]
	v_lshlrev_b32_e32 v122, 16, v195
	v_and_b32_e32 v123, 0xffff0000, v195
	v_pk_fma_f32 v[194:195], v[202:203], v[122:123], v[200:201]
	v_lshlrev_b64 v[122:123], 2, v[184:185]
	v_lshl_add_u64 v[128:129], v[218:219], 0, v[122:123]
	v_pk_mul_f32 v[118:119], v[118:119], v[220:221] op_sel_hi:[1,0]
	global_store_dwordx4 v[128:129], v[124:127], off nt
	global_store_dwordx4 v[128:129], v[192:195], off offset:16 nt
	v_pk_mul_f32 v[120:121], v[120:121], v[220:221] op_sel_hi:[1,0]
	v_pk_mul_f32 v[124:125], v[116:117], v[220:221] op_sel_hi:[1,0]
	v_mul_f32_e32 v116, 0xbfb8aa3b, v118
	v_exp_f32_e32 v118, v116
	v_mul_f32_e32 v116, 0xbfb8aa3b, v119
	v_exp_f32_e32 v119, v116
	v_pk_mul_f32 v[116:117], v[114:115], v[220:221] op_sel_hi:[1,0]
	v_add_f32_e32 v114, 1.0, v118
	v_mul_f32_e32 v120, 0xbfb8aa3b, v120
	v_add_f32_e32 v115, 1.0, v119
	v_mul_f32_e32 v121, 0xbfb8aa3b, v121
	v_rcp_f32_e32 v114, v114
	v_rcp_f32_e32 v115, v115
	v_exp_f32_e32 v120, v120
	v_exp_f32_e32 v121, v121
	v_lshlrev_b32_e32 v118, 16, v214
	v_and_b32_e32 v119, 0xffff0000, v214
	v_pk_fma_f32 v[114:115], v[114:115], v[118:119], v[210:211]
	v_add_f32_e32 v118, 1.0, v120
	v_add_f32_e32 v119, 1.0, v121
	v_rcp_f32_e32 v118, v118
	v_rcp_f32_e32 v119, v119
	v_mul_f32_e32 v116, 0xbfb8aa3b, v116
	v_lshlrev_b32_e32 v120, 16, v215
	v_and_b32_e32 v121, 0xffff0000, v215
	v_exp_f32_e32 v126, v116
	v_mul_f32_e32 v116, 0xbfb8aa3b, v117
	v_exp_f32_e32 v127, v116
	v_pk_fma_f32 v[116:117], v[118:119], v[120:121], v[212:213]
	v_mul_f32_e32 v121, 0xbfb8aa3b, v124
	v_exp_f32_e32 v124, v121
	v_mul_f32_e32 v121, 0xbfb8aa3b, v125
	v_exp_f32_e32 v125, v121
	v_add_f32_e32 v118, 1.0, v126
	v_add_f32_e32 v119, 1.0, v127
	v_rcp_f32_e32 v118, v118
	v_rcp_f32_e32 v119, v119
	v_add_f32_e32 v124, 1.0, v124
	v_add_f32_e32 v125, 1.0, v125
	v_rcp_f32_e32 v124, v124
	v_rcp_f32_e32 v125, v125
	v_lshlrev_b32_e32 v120, 16, v216
	v_and_b32_e32 v121, 0xffff0000, v216
	v_pk_fma_f32 v[118:119], v[118:119], v[120:121], v[206:207]
	v_lshlrev_b32_e32 v120, 16, v217
	v_and_b32_e32 v121, 0xffff0000, v217
	v_pk_mul_f32 v[110:111], v[110:111], v[188:189] op_sel_hi:[1,0]
	v_pk_fma_f32 v[120:121], v[124:125], v[120:121], v[208:209]
	global_store_dwordx4 v[128:129], v[114:117], off offset:512 nt
	global_store_dwordx4 v[128:129], v[118:121], off offset:528 nt
	v_pk_mul_f32 v[112:113], v[112:113], v[188:189] op_sel_hi:[1,0]
	v_pk_mul_f32 v[116:117], v[108:109], v[188:189] op_sel_hi:[1,0]
	v_mul_f32_e32 v108, 0xbfb8aa3b, v110
	v_exp_f32_e32 v110, v108
	v_mul_f32_e32 v108, 0xbfb8aa3b, v111
	v_exp_f32_e32 v111, v108
	v_pk_mul_f32 v[108:109], v[106:107], v[188:189] op_sel_hi:[1,0]
	v_add_f32_e32 v106, 1.0, v110
	v_mul_f32_e32 v112, 0xbfb8aa3b, v112
	v_add_f32_e32 v107, 1.0, v111
	v_mul_f32_e32 v113, 0xbfb8aa3b, v113
	v_rcp_f32_e32 v106, v106
	v_rcp_f32_e32 v107, v107
	v_exp_f32_e32 v112, v112
	v_exp_f32_e32 v113, v113
	s_waitcnt vmcnt(5)
	v_lshlrev_b32_e32 v110, 16, v170
	v_and_b32_e32 v111, 0xffff0000, v170
	v_pk_fma_f32 v[106:107], v[106:107], v[110:111], v[174:175]
	v_add_f32_e32 v110, 1.0, v112
	v_add_f32_e32 v111, 1.0, v113
	v_rcp_f32_e32 v110, v110
	v_rcp_f32_e32 v111, v111
	v_mul_f32_e32 v108, 0xbfb8aa3b, v108
	v_lshlrev_b32_e32 v112, 16, v171
	v_and_b32_e32 v113, 0xffff0000, v171
	v_exp_f32_e32 v118, v108
	v_mul_f32_e32 v108, 0xbfb8aa3b, v109
	v_exp_f32_e32 v119, v108
	v_pk_fma_f32 v[108:109], v[110:111], v[112:113], v[176:177]
	v_mul_f32_e32 v113, 0xbfb8aa3b, v116
	v_exp_f32_e32 v116, v113
	v_mul_f32_e32 v113, 0xbfb8aa3b, v117
	v_exp_f32_e32 v117, v113
	v_add_f32_e32 v110, 1.0, v118
	v_add_f32_e32 v111, 1.0, v119
	v_rcp_f32_e32 v110, v110
	v_rcp_f32_e32 v111, v111
	v_add_f32_e32 v116, 1.0, v116
	v_add_f32_e32 v117, 1.0, v117
	v_rcp_f32_e32 v116, v116
	v_rcp_f32_e32 v117, v117
	v_lshlrev_b64 v[114:115], 12, v[190:191]
	v_lshl_add_u64 v[114:115], s[22:23], 0, v[114:115]
	v_lshlrev_b32_e32 v112, 16, v172
	v_and_b32_e32 v113, 0xffff0000, v172
	v_pk_fma_f32 v[110:111], v[110:111], v[112:113], v[166:167]
	v_lshlrev_b32_e32 v112, 16, v173
	v_and_b32_e32 v113, 0xffff0000, v173
	v_lshl_add_u64 v[114:115], v[114:115], 0, v[122:123]
	v_pk_mul_f32 v[102:103], v[102:103], v[188:189] op_sel_hi:[1,0]
	v_pk_fma_f32 v[112:113], v[116:117], v[112:113], v[168:169]
	global_store_dwordx4 v[114:115], v[106:109], off nt
	global_store_dwordx4 v[114:115], v[110:113], off offset:16 nt
	v_pk_mul_f32 v[104:105], v[104:105], v[188:189] op_sel_hi:[1,0]
	v_pk_mul_f32 v[106:107], v[100:101], v[188:189] op_sel_hi:[1,0]
	v_mul_f32_e32 v100, 0xbfb8aa3b, v102
	v_exp_f32_e32 v102, v100
	v_mul_f32_e32 v100, 0xbfb8aa3b, v103
	v_exp_f32_e32 v103, v100
	v_pk_mul_f32 v[100:101], v[98:99], v[188:189] op_sel_hi:[1,0]
	v_add_f32_e32 v98, 1.0, v102
	v_mul_f32_e32 v104, 0xbfb8aa3b, v104
	v_add_f32_e32 v99, 1.0, v103
	v_mul_f32_e32 v105, 0xbfb8aa3b, v105
	v_rcp_f32_e32 v98, v98
	v_rcp_f32_e32 v99, v99
	v_exp_f32_e32 v104, v104
	v_exp_f32_e32 v105, v105
	s_waitcnt vmcnt(6)
	v_lshlrev_b32_e32 v102, 16, v158
	v_and_b32_e32 v103, 0xffff0000, v158
	v_pk_fma_f32 v[98:99], v[98:99], v[102:103], v[162:163]
	v_add_f32_e32 v102, 1.0, v104
	v_add_f32_e32 v103, 1.0, v105
	v_rcp_f32_e32 v102, v102
	v_rcp_f32_e32 v103, v103
	v_mul_f32_e32 v100, 0xbfb8aa3b, v100
	v_lshlrev_b32_e32 v104, 16, v159
	v_and_b32_e32 v105, 0xffff0000, v159
	v_exp_f32_e32 v108, v100
	v_mul_f32_e32 v100, 0xbfb8aa3b, v101
	v_exp_f32_e32 v109, v100
	v_pk_fma_f32 v[100:101], v[102:103], v[104:105], v[164:165]
	v_mul_f32_e32 v105, 0xbfb8aa3b, v106
	v_exp_f32_e32 v106, v105
	v_mul_f32_e32 v105, 0xbfb8aa3b, v107
	v_exp_f32_e32 v107, v105
	v_add_f32_e32 v102, 1.0, v108
	v_add_f32_e32 v103, 1.0, v109
	v_rcp_f32_e32 v102, v102
	v_rcp_f32_e32 v103, v103
	v_add_f32_e32 v106, 1.0, v106
	v_add_f32_e32 v107, 1.0, v107
	v_rcp_f32_e32 v106, v106
	v_rcp_f32_e32 v107, v107
	v_lshlrev_b32_e32 v104, 16, v160
	v_and_b32_e32 v105, 0xffff0000, v160
	v_or_b32_e32 v166, 32, v186
	v_pk_fma_f32 v[102:103], v[102:103], v[104:105], v[154:155]
	v_lshlrev_b32_e32 v104, 16, v161
	v_and_b32_e32 v105, 0xffff0000, v161
	v_ashrrev_i32_e32 v167, 31, v166
	v_pk_fma_f32 v[104:105], v[106:107], v[104:105], v[156:157]
	global_store_dwordx4 v[114:115], v[98:101], off offset:512 nt
	global_store_dwordx4 v[114:115], v[102:105], off offset:528 nt
	v_or_b32_e32 v170, 48, v186
	v_lshlrev_b64 v[98:99], 10, v[166:167]
	v_lshl_add_u64 v[98:99], v[98:99], 0, v[184:185]
	v_lshlrev_b64 v[100:101], 1, v[98:99]
	v_lshl_add_u64 v[102:103], s[24:25], 0, v[100:101]
	global_load_dwordx4 v[126:129], v[102:103], off
	v_lshl_add_u64 v[98:99], v[98:99], 2, s[22:23]
	global_load_dwordx4 v[154:157], v[98:99], off
	v_mov_b32_e32 v102, v151
	v_mov_b32_e32 v103, v152
	v_mov_b32_e32 v151, v153
	v_pk_add_f32 v[102:103], v[102:103], v[150:151]
	global_load_dwordx4 v[150:153], v[98:99], off offset:16
	v_add_f32_e32 v102, v102, v103
	ds_swizzle_b32 v103, v102 offset:swizzle(SWAP,16)
	v_or_b32_e32 v100, 0x100, v100
	v_ashrrev_i32_e32 v171, 31, v170
	v_lshlrev_b64 v[166:167], 12, v[166:167]
	v_lshl_add_u64 v[166:167], s[22:23], 0, v[166:167]
	s_waitcnt lgkmcnt(0)
	v_add_f32_e32 v104, v102, v103
	v_mov_b32_e32 v102, v147
	v_mov_b32_e32 v103, v148
	v_mov_b32_e32 v147, v149
	v_pk_add_f32 v[102:103], v[102:103], v[146:147]
	global_load_dwordx4 v[146:149], v[98:99], off offset:528
	global_load_dwordx4 v[158:161], v[98:99], off offset:512
	v_lshl_add_u64 v[98:99], s[24:25], 0, v[100:101]
	global_load_dwordx4 v[162:165], v[98:99], off
	v_add_f32_e32 v102, v102, v103
	ds_swizzle_b32 v103, v102 offset:swizzle(SWAP,16)
	v_mov_b32_e32 v105, v104
	s_nop 1
	v_permlane32_swap_b32_e32 v104, v105
	v_add_f32_e32 v104, v104, v105
	s_waitcnt lgkmcnt(0)
	v_add_f32_e32 v102, v102, v103
	v_mov_b32_e32 v103, v102
	s_nop 1
	v_permlane32_swap_b32_e32 v102, v103
	v_lshlrev_b64 v[98:99], 10, v[170:171]
	v_fmamk_f32 v104, v104, 0x3a800000, v254
	v_add_f32_e32 v102, v102, v103
	v_lshl_add_u64 v[98:99], v[98:99], 0, v[184:185]
	v_rsq_f32_e32 v168, v104
	v_fmamk_f32 v102, v102, 0x3a800000, v254
	v_lshlrev_b64 v[104:105], 1, v[98:99]
	v_rsq_f32_e32 v124, v102
	v_lshl_add_u64 v[102:103], v[98:99], 2, s[22:23]
	v_lshl_add_u64 v[114:115], s[24:25], 0, v[104:105]
	v_or_b32_e32 v104, 0x100, v104
	global_load_dwordx4 v[110:113], v[102:103], off offset:16
	global_load_dwordx4 v[118:121], v[102:103], off
	global_load_dwordx4 v[98:101], v[102:103], off offset:528
	global_load_dwordx4 v[106:109], v[102:103], off offset:512
	v_lshl_add_u64 v[102:103], s[24:25], 0, v[104:105]
	global_load_dwordx4 v[114:117], v[114:115], off
	s_nop 0
	global_load_dwordx4 v[102:105], v[102:103], off
	v_pk_mul_f32 v[94:95], v[94:95], v[168:169] op_sel_hi:[1,0]
	v_pk_mul_f32 v[172:173], v[92:93], v[168:169] op_sel_hi:[1,0]
	v_mul_f32_e32 v92, 0xbfb8aa3b, v94
	v_exp_f32_e32 v94, v92
	v_mul_f32_e32 v92, 0xbfb8aa3b, v95
	v_exp_f32_e32 v95, v92
	v_pk_mul_f32 v[96:97], v[96:97], v[168:169] op_sel_hi:[1,0]
	v_pk_mul_f32 v[92:93], v[90:91], v[168:169] op_sel_hi:[1,0]
	v_add_f32_e32 v90, 1.0, v94
	v_add_f32_e32 v91, 1.0, v95
	v_mul_f32_e32 v96, 0xbfb8aa3b, v96
	v_mul_f32_e32 v97, 0xbfb8aa3b, v97
	v_rcp_f32_e32 v90, v90
	v_rcp_f32_e32 v91, v91
	v_exp_f32_e32 v96, v96
	v_exp_f32_e32 v97, v97
	v_mul_f32_e32 v92, 0xbfb8aa3b, v92
	v_exp_f32_e32 v125, v92
	v_mul_f32_e32 v92, 0xbfb8aa3b, v93
	v_pk_mul_f32 v[86:87], v[86:87], v[168:169] op_sel_hi:[1,0]
	v_pk_mul_f32 v[88:89], v[88:89], v[168:169] op_sel_hi:[1,0]
	s_waitcnt vmcnt(11)
	v_lshlrev_b32_e32 v94, 16, v126
	v_and_b32_e32 v95, 0xffff0000, v126
	s_waitcnt vmcnt(10)
	v_pk_fma_f32 v[90:91], v[90:91], v[94:95], v[154:155]
	v_add_f32_e32 v94, 1.0, v96
	v_add_f32_e32 v95, 1.0, v97
	v_rcp_f32_e32 v94, v94
	v_rcp_f32_e32 v95, v95
	v_lshlrev_b32_e32 v96, 16, v127
	v_and_b32_e32 v97, 0xffff0000, v127
	v_exp_f32_e32 v126, v92
	v_pk_fma_f32 v[92:93], v[94:95], v[96:97], v[156:157]
	v_mul_f32_e32 v97, 0xbfb8aa3b, v172
	v_add_f32_e32 v94, 1.0, v125
	v_exp_f32_e32 v125, v97
	v_mul_f32_e32 v97, 0xbfb8aa3b, v173
	v_exp_f32_e32 v127, v97
	v_add_f32_e32 v95, 1.0, v126
	v_add_f32_e32 v125, 1.0, v125
	v_rcp_f32_e32 v94, v94
	v_rcp_f32_e32 v95, v95
	v_rcp_f32_e32 v126, v125
	v_add_f32_e32 v125, 1.0, v127
	v_rcp_f32_e32 v127, v125
	v_lshlrev_b32_e32 v96, 16, v128
	v_and_b32_e32 v97, 0xffff0000, v128
	s_waitcnt vmcnt(9)
	v_pk_fma_f32 v[94:95], v[94:95], v[96:97], v[150:151]
	v_lshlrev_b32_e32 v96, 16, v129
	v_and_b32_e32 v97, 0xffff0000, v129
	v_pk_fma_f32 v[96:97], v[126:127], v[96:97], v[152:153]
	v_lshl_add_u64 v[126:127], v[166:167], 0, v[122:123]
	global_store_dwordx4 v[126:127], v[90:93], off nt
	global_store_dwordx4 v[126:127], v[94:97], off offset:16 nt
	v_mul_f32_e32 v88, 0xbfb8aa3b, v88
	v_pk_mul_f32 v[90:91], v[84:85], v[168:169] op_sel_hi:[1,0]
	v_mul_f32_e32 v84, 0xbfb8aa3b, v86
	v_exp_f32_e32 v86, v84
	v_mul_f32_e32 v84, 0xbfb8aa3b, v87
	v_exp_f32_e32 v87, v84
	v_pk_mul_f32 v[84:85], v[82:83], v[168:169] op_sel_hi:[1,0]
	v_add_f32_e32 v82, 1.0, v86
	v_mul_f32_e32 v89, 0xbfb8aa3b, v89
	v_add_f32_e32 v83, 1.0, v87
	v_rcp_f32_e32 v82, v82
	v_rcp_f32_e32 v83, v83
	v_exp_f32_e32 v88, v88
	v_exp_f32_e32 v89, v89
	s_waitcnt vmcnt(8)
	v_lshlrev_b32_e32 v86, 16, v162
	v_and_b32_e32 v87, 0xffff0000, v162
	v_pk_fma_f32 v[82:83], v[82:83], v[86:87], v[158:159]
	v_add_f32_e32 v86, 1.0, v88
	v_add_f32_e32 v87, 1.0, v89
	v_rcp_f32_e32 v86, v86
	v_rcp_f32_e32 v87, v87
	v_mul_f32_e32 v84, 0xbfb8aa3b, v84
	v_lshlrev_b32_e32 v88, 16, v163
	v_and_b32_e32 v89, 0xffff0000, v163
	v_exp_f32_e32 v92, v84
	v_mul_f32_e32 v84, 0xbfb8aa3b, v85
	v_exp_f32_e32 v93, v84
	v_pk_fma_f32 v[84:85], v[86:87], v[88:89], v[160:161]
	v_mul_f32_e32 v89, 0xbfb8aa3b, v90
	v_exp_f32_e32 v90, v89
	v_mul_f32_e32 v89, 0xbfb8aa3b, v91
	v_exp_f32_e32 v91, v89
	v_add_f32_e32 v86, 1.0, v92
	v_add_f32_e32 v87, 1.0, v93
	v_rcp_f32_e32 v86, v86
	v_rcp_f32_e32 v87, v87
	v_add_f32_e32 v90, 1.0, v90
	v_add_f32_e32 v91, 1.0, v91
	v_rcp_f32_e32 v90, v90
	v_rcp_f32_e32 v91, v91
	v_lshlrev_b32_e32 v88, 16, v164
	v_and_b32_e32 v89, 0xffff0000, v164
	v_pk_fma_f32 v[86:87], v[86:87], v[88:89], v[146:147]
	v_lshlrev_b32_e32 v88, 16, v165
	v_and_b32_e32 v89, 0xffff0000, v165
	v_pk_mul_f32 v[78:79], v[78:79], v[124:125] op_sel_hi:[1,0]
	v_pk_fma_f32 v[88:89], v[90:91], v[88:89], v[148:149]
	global_store_dwordx4 v[126:127], v[82:85], off offset:512 nt
	global_store_dwordx4 v[126:127], v[86:89], off offset:528 nt
	v_pk_mul_f32 v[80:81], v[80:81], v[124:125] op_sel_hi:[1,0]
	v_pk_mul_f32 v[84:85], v[76:77], v[124:125] op_sel_hi:[1,0]
	v_mul_f32_e32 v76, 0xbfb8aa3b, v78
	v_exp_f32_e32 v78, v76
	v_mul_f32_e32 v76, 0xbfb8aa3b, v79
	v_exp_f32_e32 v79, v76
	v_pk_mul_f32 v[76:77], v[74:75], v[124:125] op_sel_hi:[1,0]
	v_add_f32_e32 v74, 1.0, v78
	v_mul_f32_e32 v80, 0xbfb8aa3b, v80
	v_add_f32_e32 v75, 1.0, v79
	v_mul_f32_e32 v81, 0xbfb8aa3b, v81
	v_rcp_f32_e32 v74, v74
	v_rcp_f32_e32 v75, v75
	v_exp_f32_e32 v80, v80
	v_exp_f32_e32 v81, v81
	s_waitcnt vmcnt(5)
	v_lshlrev_b32_e32 v78, 16, v114
	v_and_b32_e32 v79, 0xffff0000, v114
	v_pk_fma_f32 v[74:75], v[74:75], v[78:79], v[118:119]
	v_add_f32_e32 v78, 1.0, v80
	v_add_f32_e32 v79, 1.0, v81
	v_rcp_f32_e32 v78, v78
	v_rcp_f32_e32 v79, v79
	v_mul_f32_e32 v76, 0xbfb8aa3b, v76
	v_lshlrev_b32_e32 v80, 16, v115
	v_and_b32_e32 v81, 0xffff0000, v115
	v_exp_f32_e32 v86, v76
	v_mul_f32_e32 v76, 0xbfb8aa3b, v77
	v_exp_f32_e32 v87, v76
	v_pk_fma_f32 v[76:77], v[78:79], v[80:81], v[120:121]
	v_mul_f32_e32 v81, 0xbfb8aa3b, v84
	v_exp_f32_e32 v84, v81
	v_mul_f32_e32 v81, 0xbfb8aa3b, v85
	v_exp_f32_e32 v85, v81
	v_add_f32_e32 v78, 1.0, v86
	v_add_f32_e32 v79, 1.0, v87
	v_rcp_f32_e32 v78, v78
	v_rcp_f32_e32 v79, v79
	v_add_f32_e32 v84, 1.0, v84
	v_add_f32_e32 v85, 1.0, v85
	v_rcp_f32_e32 v84, v84
	v_rcp_f32_e32 v85, v85
	v_lshlrev_b64 v[82:83], 12, v[170:171]
	v_lshl_add_u64 v[82:83], s[22:23], 0, v[82:83]
	v_lshlrev_b32_e32 v80, 16, v116
	v_and_b32_e32 v81, 0xffff0000, v116
	v_pk_fma_f32 v[78:79], v[78:79], v[80:81], v[110:111]
	v_lshlrev_b32_e32 v80, 16, v117
	v_and_b32_e32 v81, 0xffff0000, v117
	v_lshl_add_u64 v[82:83], v[82:83], 0, v[122:123]
	v_pk_mul_f32 v[70:71], v[70:71], v[124:125] op_sel_hi:[1,0]
	v_pk_fma_f32 v[80:81], v[84:85], v[80:81], v[112:113]
	global_store_dwordx4 v[82:83], v[74:77], off nt
	global_store_dwordx4 v[82:83], v[78:81], off offset:16 nt
	v_pk_mul_f32 v[72:73], v[72:73], v[124:125] op_sel_hi:[1,0]
	v_pk_mul_f32 v[74:75], v[68:69], v[124:125] op_sel_hi:[1,0]
	v_mul_f32_e32 v68, 0xbfb8aa3b, v70
	v_exp_f32_e32 v70, v68
	v_mul_f32_e32 v68, 0xbfb8aa3b, v71
	v_exp_f32_e32 v71, v68
	v_pk_mul_f32 v[68:69], v[66:67], v[124:125] op_sel_hi:[1,0]
	v_add_f32_e32 v66, 1.0, v70
	v_mul_f32_e32 v72, 0xbfb8aa3b, v72
	v_add_f32_e32 v67, 1.0, v71
	v_mul_f32_e32 v73, 0xbfb8aa3b, v73
	v_rcp_f32_e32 v66, v66
	v_rcp_f32_e32 v67, v67
	v_exp_f32_e32 v72, v72
	v_exp_f32_e32 v73, v73
	s_waitcnt vmcnt(6)
	v_lshlrev_b32_e32 v70, 16, v102
	v_and_b32_e32 v71, 0xffff0000, v102
	v_pk_fma_f32 v[66:67], v[66:67], v[70:71], v[106:107]
	v_add_f32_e32 v70, 1.0, v72
	v_add_f32_e32 v71, 1.0, v73
	v_rcp_f32_e32 v70, v70
	v_rcp_f32_e32 v71, v71
	v_mul_f32_e32 v68, 0xbfb8aa3b, v68
	v_lshlrev_b32_e32 v72, 16, v103
	v_and_b32_e32 v73, 0xffff0000, v103
	v_exp_f32_e32 v76, v68
	v_mul_f32_e32 v68, 0xbfb8aa3b, v69
	v_exp_f32_e32 v77, v68
	v_pk_fma_f32 v[68:69], v[70:71], v[72:73], v[108:109]
	v_mul_f32_e32 v73, 0xbfb8aa3b, v74
	v_exp_f32_e32 v74, v73
	v_mul_f32_e32 v73, 0xbfb8aa3b, v75
	v_exp_f32_e32 v75, v73
	v_add_f32_e32 v70, 1.0, v76
	v_add_f32_e32 v71, 1.0, v77
	v_rcp_f32_e32 v70, v70
	v_rcp_f32_e32 v71, v71
	v_add_f32_e32 v74, 1.0, v74
	v_add_f32_e32 v75, 1.0, v75
	v_rcp_f32_e32 v74, v74
	v_rcp_f32_e32 v75, v75
	v_lshlrev_b32_e32 v72, 16, v104
	v_and_b32_e32 v73, 0xffff0000, v104
	v_add_u32_e32 v116, 0x80, v186
	v_pk_fma_f32 v[70:71], v[70:71], v[72:73], v[98:99]
	v_lshlrev_b32_e32 v72, 16, v105
	v_and_b32_e32 v73, 0xffff0000, v105
	v_ashrrev_i32_e32 v117, 31, v116
	v_pk_fma_f32 v[72:73], v[74:75], v[72:73], v[100:101]
	global_store_dwordx4 v[82:83], v[66:69], off offset:512 nt
	global_store_dwordx4 v[82:83], v[70:73], off offset:528 nt
	v_add_u32_e32 v120, 0x90, v186
	v_lshlrev_b64 v[66:67], 10, v[116:117]
	v_lshl_add_u64 v[66:67], v[66:67], 0, v[184:185]
	v_lshlrev_b64 v[68:69], 1, v[66:67]
	v_lshl_add_u64 v[70:71], s[24:25], 0, v[68:69]
	global_load_dwordx4 v[92:95], v[70:71], off
	v_lshl_add_u64 v[66:67], v[66:67], 2, s[22:23]
	global_load_dwordx4 v[96:99], v[66:67], off
	global_load_dwordx4 v[100:103], v[66:67], off offset:16
	v_or_b32_e32 v68, 0x100, v68
	global_load_dwordx4 v[104:107], v[66:67], off offset:528
	global_load_dwordx4 v[108:111], v[66:67], off offset:512
	v_lshl_add_u64 v[66:67], s[24:25], 0, v[68:69]
	global_load_dwordx4 v[112:115], v[66:67], off
	v_mov_b32_e32 v70, v143
	v_mov_b32_e32 v71, v144
	v_mov_b32_e32 v143, v145
	v_pk_add_f32 v[70:71], v[70:71], v[142:143]
	v_ashrrev_i32_e32 v121, 31, v120
	v_add_f32_e32 v70, v70, v71
	ds_swizzle_b32 v71, v70 offset:swizzle(SWAP,16)
	v_lshlrev_b64 v[66:67], 10, v[120:121]
	v_lshl_add_u64 v[66:67], v[66:67], 0, v[184:185]
	v_lshlrev_b64 v[116:117], 12, v[116:117]
	v_lshl_add_u64 v[116:117], s[22:23], 0, v[116:117]
	s_waitcnt lgkmcnt(0)
	v_add_f32_e32 v72, v70, v71
	v_mov_b32_e32 v70, v139
	v_mov_b32_e32 v71, v140
	v_mov_b32_e32 v139, v141
	v_pk_add_f32 v[70:71], v[70:71], v[138:139]
	v_mov_b32_e32 v73, v72
	v_add_f32_e32 v70, v70, v71
	ds_swizzle_b32 v71, v70 offset:swizzle(SWAP,16)
	v_permlane32_swap_b32_e32 v72, v73
	v_add_f32_e32 v72, v72, v73
	v_fmamk_f32 v72, v72, 0x3a800000, v254
	s_waitcnt lgkmcnt(0)
	v_add_f32_e32 v70, v70, v71
	v_mov_b32_e32 v71, v70
	s_nop 1
	v_permlane32_swap_b32_e32 v70, v71
	v_add_f32_e32 v70, v70, v71
	v_rsq_f32_e32 v118, v72
	v_fmamk_f32 v70, v70, 0x3a800000, v254
	v_lshlrev_b64 v[72:73], 1, v[66:67]
	v_rsq_f32_e32 v90, v70
	v_lshl_add_u64 v[70:71], v[66:67], 2, s[22:23]
	v_lshl_add_u64 v[82:83], s[24:25], 0, v[72:73]
	v_or_b32_e32 v72, 0x100, v72
	global_load_dwordx4 v[78:81], v[70:71], off offset:16
	global_load_dwordx4 v[86:89], v[70:71], off
	global_load_dwordx4 v[66:69], v[70:71], off offset:528
	global_load_dwordx4 v[74:77], v[70:71], off offset:512
	v_lshl_add_u64 v[70:71], s[24:25], 0, v[72:73]
	global_load_dwordx4 v[82:85], v[82:83], off
	s_nop 0
	global_load_dwordx4 v[70:73], v[70:71], off
	v_pk_mul_f32 v[62:63], v[62:63], v[118:119] op_sel_hi:[1,0]
	v_pk_mul_f32 v[124:125], v[60:61], v[118:119] op_sel_hi:[1,0]
	v_mul_f32_e32 v60, 0xbfb8aa3b, v62
	v_exp_f32_e32 v62, v60
	v_mul_f32_e32 v60, 0xbfb8aa3b, v63
	v_exp_f32_e32 v63, v60
	v_pk_mul_f32 v[64:65], v[64:65], v[118:119] op_sel_hi:[1,0]
	v_pk_mul_f32 v[60:61], v[58:59], v[118:119] op_sel_hi:[1,0]
	v_add_f32_e32 v58, 1.0, v62
	v_add_f32_e32 v59, 1.0, v63
	v_mul_f32_e32 v64, 0xbfb8aa3b, v64
	v_mul_f32_e32 v65, 0xbfb8aa3b, v65
	v_rcp_f32_e32 v58, v58
	v_rcp_f32_e32 v59, v59
	v_exp_f32_e32 v64, v64
	v_exp_f32_e32 v65, v65
	v_mul_f32_e32 v60, 0xbfb8aa3b, v60
	v_exp_f32_e32 v91, v60
	v_mul_f32_e32 v60, 0xbfb8aa3b, v61
	v_pk_mul_f32 v[54:55], v[54:55], v[118:119] op_sel_hi:[1,0]
	v_pk_mul_f32 v[56:57], v[56:57], v[118:119] op_sel_hi:[1,0]
	s_waitcnt vmcnt(11)
	v_lshlrev_b32_e32 v62, 16, v92
	v_and_b32_e32 v63, 0xffff0000, v92
	s_waitcnt vmcnt(10)
	v_pk_fma_f32 v[58:59], v[58:59], v[62:63], v[96:97]
	v_add_f32_e32 v62, 1.0, v64
	v_add_f32_e32 v63, 1.0, v65
	v_rcp_f32_e32 v62, v62
	v_rcp_f32_e32 v63, v63
	v_lshlrev_b32_e32 v64, 16, v93
	v_and_b32_e32 v65, 0xffff0000, v93
	v_exp_f32_e32 v92, v60
	v_pk_fma_f32 v[60:61], v[62:63], v[64:65], v[98:99]
	v_mul_f32_e32 v65, 0xbfb8aa3b, v124
	v_add_f32_e32 v62, 1.0, v91
	v_exp_f32_e32 v91, v65
	v_mul_f32_e32 v65, 0xbfb8aa3b, v125
	v_exp_f32_e32 v93, v65
	v_add_f32_e32 v63, 1.0, v92
	v_add_f32_e32 v91, 1.0, v91
	v_rcp_f32_e32 v62, v62
	v_rcp_f32_e32 v63, v63
	v_rcp_f32_e32 v92, v91
	v_add_f32_e32 v91, 1.0, v93
	v_rcp_f32_e32 v93, v91
	v_lshlrev_b32_e32 v64, 16, v94
	v_and_b32_e32 v65, 0xffff0000, v94
	s_waitcnt vmcnt(9)
	v_pk_fma_f32 v[62:63], v[62:63], v[64:65], v[100:101]
	v_lshlrev_b32_e32 v64, 16, v95
	v_and_b32_e32 v65, 0xffff0000, v95
	v_pk_fma_f32 v[64:65], v[92:93], v[64:65], v[102:103]
	v_lshl_add_u64 v[92:93], v[116:117], 0, v[122:123]
	global_store_dwordx4 v[92:93], v[58:61], off nt
	global_store_dwordx4 v[92:93], v[62:65], off offset:16 nt
	v_mul_f32_e32 v56, 0xbfb8aa3b, v56
	v_pk_mul_f32 v[58:59], v[52:53], v[118:119] op_sel_hi:[1,0]
	v_mul_f32_e32 v52, 0xbfb8aa3b, v54
	v_exp_f32_e32 v54, v52
	v_mul_f32_e32 v52, 0xbfb8aa3b, v55
	v_exp_f32_e32 v55, v52
	v_pk_mul_f32 v[52:53], v[50:51], v[118:119] op_sel_hi:[1,0]
	v_add_f32_e32 v50, 1.0, v54
	v_mul_f32_e32 v57, 0xbfb8aa3b, v57
	v_add_f32_e32 v51, 1.0, v55
	v_rcp_f32_e32 v50, v50
	v_rcp_f32_e32 v51, v51
	v_exp_f32_e32 v56, v56
	v_exp_f32_e32 v57, v57
	s_waitcnt vmcnt(8)
	v_lshlrev_b32_e32 v54, 16, v112
	v_and_b32_e32 v55, 0xffff0000, v112
	v_pk_fma_f32 v[50:51], v[50:51], v[54:55], v[108:109]
	v_add_f32_e32 v54, 1.0, v56
	v_add_f32_e32 v55, 1.0, v57
	v_rcp_f32_e32 v54, v54
	v_rcp_f32_e32 v55, v55
	v_mul_f32_e32 v52, 0xbfb8aa3b, v52
	v_lshlrev_b32_e32 v56, 16, v113
	v_and_b32_e32 v57, 0xffff0000, v113
	v_exp_f32_e32 v60, v52
	v_mul_f32_e32 v52, 0xbfb8aa3b, v53
	v_exp_f32_e32 v61, v52
	v_pk_fma_f32 v[52:53], v[54:55], v[56:57], v[110:111]
	v_mul_f32_e32 v57, 0xbfb8aa3b, v58
	v_exp_f32_e32 v58, v57
	v_mul_f32_e32 v57, 0xbfb8aa3b, v59
	v_exp_f32_e32 v59, v57
	v_add_f32_e32 v54, 1.0, v60
	v_add_f32_e32 v55, 1.0, v61
	v_rcp_f32_e32 v54, v54
	v_rcp_f32_e32 v55, v55
	v_add_f32_e32 v58, 1.0, v58
	v_add_f32_e32 v59, 1.0, v59
	v_rcp_f32_e32 v58, v58
	v_rcp_f32_e32 v59, v59
	v_lshlrev_b32_e32 v56, 16, v114
	v_and_b32_e32 v57, 0xffff0000, v114
	v_pk_fma_f32 v[54:55], v[54:55], v[56:57], v[104:105]
	v_lshlrev_b32_e32 v56, 16, v115
	v_and_b32_e32 v57, 0xffff0000, v115
	v_pk_mul_f32 v[46:47], v[46:47], v[90:91] op_sel_hi:[1,0]
	v_pk_fma_f32 v[56:57], v[58:59], v[56:57], v[106:107]
	global_store_dwordx4 v[92:93], v[50:53], off offset:512 nt
	global_store_dwordx4 v[92:93], v[54:57], off offset:528 nt
	v_pk_mul_f32 v[48:49], v[48:49], v[90:91] op_sel_hi:[1,0]
	v_pk_mul_f32 v[52:53], v[44:45], v[90:91] op_sel_hi:[1,0]
	v_mul_f32_e32 v44, 0xbfb8aa3b, v46
	v_exp_f32_e32 v46, v44
	v_mul_f32_e32 v44, 0xbfb8aa3b, v47
	v_exp_f32_e32 v47, v44
	v_pk_mul_f32 v[44:45], v[42:43], v[90:91] op_sel_hi:[1,0]
	v_add_f32_e32 v42, 1.0, v46
	v_mul_f32_e32 v48, 0xbfb8aa3b, v48
	v_add_f32_e32 v43, 1.0, v47
	v_mul_f32_e32 v49, 0xbfb8aa3b, v49
	v_rcp_f32_e32 v42, v42
	v_rcp_f32_e32 v43, v43
	v_exp_f32_e32 v48, v48
	v_exp_f32_e32 v49, v49
	s_waitcnt vmcnt(5)
	v_lshlrev_b32_e32 v46, 16, v82
	v_and_b32_e32 v47, 0xffff0000, v82
	v_pk_fma_f32 v[42:43], v[42:43], v[46:47], v[86:87]
	v_add_f32_e32 v46, 1.0, v48
	v_add_f32_e32 v47, 1.0, v49
	v_rcp_f32_e32 v46, v46
	v_rcp_f32_e32 v47, v47
	v_mul_f32_e32 v44, 0xbfb8aa3b, v44
	v_lshlrev_b32_e32 v48, 16, v83
	v_and_b32_e32 v49, 0xffff0000, v83
	v_exp_f32_e32 v54, v44
	v_mul_f32_e32 v44, 0xbfb8aa3b, v45
	v_exp_f32_e32 v55, v44
	v_pk_fma_f32 v[44:45], v[46:47], v[48:49], v[88:89]
	v_mul_f32_e32 v49, 0xbfb8aa3b, v52
	v_exp_f32_e32 v52, v49
	v_mul_f32_e32 v49, 0xbfb8aa3b, v53
	v_exp_f32_e32 v53, v49
	v_add_f32_e32 v46, 1.0, v54
	v_add_f32_e32 v47, 1.0, v55
	v_rcp_f32_e32 v46, v46
	v_rcp_f32_e32 v47, v47
	v_add_f32_e32 v52, 1.0, v52
	v_add_f32_e32 v53, 1.0, v53
	v_rcp_f32_e32 v52, v52
	v_rcp_f32_e32 v53, v53
	v_lshlrev_b64 v[50:51], 12, v[120:121]
	v_lshl_add_u64 v[50:51], s[22:23], 0, v[50:51]
	v_lshlrev_b32_e32 v48, 16, v84
	v_and_b32_e32 v49, 0xffff0000, v84
	v_pk_fma_f32 v[46:47], v[46:47], v[48:49], v[78:79]
	v_lshlrev_b32_e32 v48, 16, v85
	v_and_b32_e32 v49, 0xffff0000, v85
	v_lshl_add_u64 v[50:51], v[50:51], 0, v[122:123]
	v_pk_mul_f32 v[38:39], v[38:39], v[90:91] op_sel_hi:[1,0]
	v_pk_fma_f32 v[48:49], v[52:53], v[48:49], v[80:81]
	global_store_dwordx4 v[50:51], v[42:45], off nt
	global_store_dwordx4 v[50:51], v[46:49], off offset:16 nt
	v_pk_mul_f32 v[40:41], v[40:41], v[90:91] op_sel_hi:[1,0]
	v_pk_mul_f32 v[42:43], v[36:37], v[90:91] op_sel_hi:[1,0]
	v_mul_f32_e32 v36, 0xbfb8aa3b, v38
	v_exp_f32_e32 v38, v36
	v_mul_f32_e32 v36, 0xbfb8aa3b, v39
	v_exp_f32_e32 v39, v36
	v_pk_mul_f32 v[36:37], v[34:35], v[90:91] op_sel_hi:[1,0]
	v_add_f32_e32 v34, 1.0, v38
	v_mul_f32_e32 v40, 0xbfb8aa3b, v40
	v_add_f32_e32 v35, 1.0, v39
	v_mul_f32_e32 v41, 0xbfb8aa3b, v41
	v_rcp_f32_e32 v34, v34
	v_rcp_f32_e32 v35, v35
	v_exp_f32_e32 v40, v40
	v_exp_f32_e32 v41, v41
	s_waitcnt vmcnt(6)
	v_lshlrev_b32_e32 v38, 16, v70
	v_and_b32_e32 v39, 0xffff0000, v70
	v_pk_fma_f32 v[34:35], v[34:35], v[38:39], v[74:75]
	v_add_f32_e32 v38, 1.0, v40
	v_add_f32_e32 v39, 1.0, v41
	v_rcp_f32_e32 v38, v38
	v_rcp_f32_e32 v39, v39
	v_mul_f32_e32 v36, 0xbfb8aa3b, v36
	v_lshlrev_b32_e32 v40, 16, v71
	v_and_b32_e32 v41, 0xffff0000, v71
	v_exp_f32_e32 v44, v36
	v_mul_f32_e32 v36, 0xbfb8aa3b, v37
	v_exp_f32_e32 v45, v36
	v_pk_fma_f32 v[36:37], v[38:39], v[40:41], v[76:77]
	v_mul_f32_e32 v41, 0xbfb8aa3b, v42
	v_exp_f32_e32 v42, v41
	v_mul_f32_e32 v41, 0xbfb8aa3b, v43
	v_exp_f32_e32 v43, v41
	v_add_f32_e32 v38, 1.0, v44
	v_add_f32_e32 v39, 1.0, v45
	v_rcp_f32_e32 v38, v38
	v_rcp_f32_e32 v39, v39
	v_add_f32_e32 v42, 1.0, v42
	v_add_f32_e32 v43, 1.0, v43
	v_rcp_f32_e32 v42, v42
	v_rcp_f32_e32 v43, v43
	v_lshlrev_b32_e32 v40, 16, v72
	v_and_b32_e32 v41, 0xffff0000, v72
	v_add_u32_e32 v84, 0xa0, v186
	v_pk_fma_f32 v[38:39], v[38:39], v[40:41], v[66:67]
	v_lshlrev_b32_e32 v40, 16, v73
	v_and_b32_e32 v41, 0xffff0000, v73
	v_ashrrev_i32_e32 v85, 31, v84
	v_pk_fma_f32 v[40:41], v[42:43], v[40:41], v[68:69]
	global_store_dwordx4 v[50:51], v[34:37], off offset:512 nt
	global_store_dwordx4 v[50:51], v[38:41], off offset:528 nt
	v_add_u32_e32 v88, 0xb0, v186
	v_lshlrev_b64 v[34:35], 10, v[84:85]
	v_lshl_add_u64 v[34:35], v[34:35], 0, v[184:185]
	v_lshlrev_b64 v[36:37], 1, v[34:35]
	v_lshl_add_u64 v[38:39], s[24:25], 0, v[36:37]
	global_load_dwordx4 v[60:63], v[38:39], off
	v_lshl_add_u64 v[34:35], v[34:35], 2, s[22:23]
	global_load_dwordx4 v[64:67], v[34:35], off
	global_load_dwordx4 v[68:71], v[34:35], off offset:16
	v_or_b32_e32 v36, 0x100, v36
	global_load_dwordx4 v[72:75], v[34:35], off offset:528
	global_load_dwordx4 v[76:79], v[34:35], off offset:512
	v_lshl_add_u64 v[34:35], s[24:25], 0, v[36:37]
	global_load_dwordx4 v[80:83], v[34:35], off
	v_mov_b32_e32 v38, v135
	v_mov_b32_e32 v39, v136
	v_mov_b32_e32 v135, v137
	v_pk_add_f32 v[38:39], v[38:39], v[134:135]
	v_ashrrev_i32_e32 v89, 31, v88
	v_add_f32_e32 v38, v38, v39
	ds_swizzle_b32 v39, v38 offset:swizzle(SWAP,16)
	v_lshlrev_b64 v[34:35], 10, v[88:89]
	v_lshl_add_u64 v[34:35], v[34:35], 0, v[184:185]
	v_lshlrev_b64 v[84:85], 12, v[84:85]
	v_lshl_add_u64 v[84:85], s[22:23], 0, v[84:85]
	s_waitcnt lgkmcnt(0)
	v_add_f32_e32 v40, v38, v39
	v_mov_b32_e32 v38, v131
	v_mov_b32_e32 v39, v132
	v_mov_b32_e32 v131, v133
	v_pk_add_f32 v[38:39], v[38:39], v[130:131]
	v_mov_b32_e32 v41, v40
	v_add_f32_e32 v38, v38, v39
	ds_swizzle_b32 v39, v38 offset:swizzle(SWAP,16)
	v_permlane32_swap_b32_e32 v40, v41
	v_add_f32_e32 v40, v40, v41
	v_fmamk_f32 v40, v40, 0x3a800000, v254
	s_waitcnt lgkmcnt(0)
	v_add_f32_e32 v38, v38, v39
	v_mov_b32_e32 v39, v38
	s_nop 1
	v_permlane32_swap_b32_e32 v38, v39
	v_add_f32_e32 v38, v38, v39
	v_rsq_f32_e32 v86, v40
	v_fmamk_f32 v38, v38, 0x3a800000, v254
	v_lshlrev_b64 v[40:41], 1, v[34:35]
	v_rsq_f32_e32 v58, v38
	v_lshl_add_u64 v[38:39], v[34:35], 2, s[22:23]
	v_lshl_add_u64 v[50:51], s[24:25], 0, v[40:41]
	v_or_b32_e32 v40, 0x100, v40
	global_load_dwordx4 v[46:49], v[38:39], off offset:16
	global_load_dwordx4 v[54:57], v[38:39], off
	global_load_dwordx4 v[34:37], v[38:39], off offset:528
	global_load_dwordx4 v[42:45], v[38:39], off offset:512
	v_lshl_add_u64 v[38:39], s[24:25], 0, v[40:41]
	global_load_dwordx4 v[50:53], v[50:51], off
	s_nop 0
	global_load_dwordx4 v[38:41], v[38:39], off
	v_pk_mul_f32 v[30:31], v[30:31], v[86:87] op_sel_hi:[1,0]
	v_pk_mul_f32 v[90:91], v[28:29], v[86:87] op_sel_hi:[1,0]
	v_mul_f32_e32 v28, 0xbfb8aa3b, v30
	v_exp_f32_e32 v30, v28
	v_mul_f32_e32 v28, 0xbfb8aa3b, v31
	v_exp_f32_e32 v31, v28
	v_pk_mul_f32 v[32:33], v[32:33], v[86:87] op_sel_hi:[1,0]
	v_pk_mul_f32 v[28:29], v[26:27], v[86:87] op_sel_hi:[1,0]
	v_add_f32_e32 v26, 1.0, v30
	v_add_f32_e32 v27, 1.0, v31
	v_mul_f32_e32 v32, 0xbfb8aa3b, v32
	v_mul_f32_e32 v33, 0xbfb8aa3b, v33
	v_rcp_f32_e32 v26, v26
	v_rcp_f32_e32 v27, v27
	v_exp_f32_e32 v32, v32
	v_exp_f32_e32 v33, v33
	v_mul_f32_e32 v28, 0xbfb8aa3b, v28
	v_exp_f32_e32 v59, v28
	v_mul_f32_e32 v28, 0xbfb8aa3b, v29
	v_pk_mul_f32 v[22:23], v[22:23], v[86:87] op_sel_hi:[1,0]
	v_pk_mul_f32 v[24:25], v[24:25], v[86:87] op_sel_hi:[1,0]
	s_waitcnt vmcnt(11)
	v_lshlrev_b32_e32 v30, 16, v60
	v_and_b32_e32 v31, 0xffff0000, v60
	s_waitcnt vmcnt(10)
	v_pk_fma_f32 v[26:27], v[26:27], v[30:31], v[64:65]
	v_add_f32_e32 v30, 1.0, v32
	v_add_f32_e32 v31, 1.0, v33
	v_rcp_f32_e32 v30, v30
	v_rcp_f32_e32 v31, v31
	v_lshlrev_b32_e32 v32, 16, v61
	v_and_b32_e32 v33, 0xffff0000, v61
	v_exp_f32_e32 v60, v28
	v_pk_fma_f32 v[28:29], v[30:31], v[32:33], v[66:67]
	v_mul_f32_e32 v33, 0xbfb8aa3b, v90
	v_add_f32_e32 v30, 1.0, v59
	v_exp_f32_e32 v59, v33
	v_mul_f32_e32 v33, 0xbfb8aa3b, v91
	v_exp_f32_e32 v61, v33
	v_add_f32_e32 v31, 1.0, v60
	v_add_f32_e32 v59, 1.0, v59
	v_rcp_f32_e32 v30, v30
	v_rcp_f32_e32 v31, v31
	v_rcp_f32_e32 v60, v59
	v_add_f32_e32 v59, 1.0, v61
	v_rcp_f32_e32 v61, v59
	v_lshlrev_b32_e32 v32, 16, v62
	v_and_b32_e32 v33, 0xffff0000, v62
	s_waitcnt vmcnt(9)
	v_pk_fma_f32 v[30:31], v[30:31], v[32:33], v[68:69]
	v_lshlrev_b32_e32 v32, 16, v63
	v_and_b32_e32 v33, 0xffff0000, v63
	v_pk_fma_f32 v[32:33], v[60:61], v[32:33], v[70:71]
	v_lshl_add_u64 v[60:61], v[84:85], 0, v[122:123]
	global_store_dwordx4 v[60:61], v[26:29], off nt
	global_store_dwordx4 v[60:61], v[30:33], off offset:16 nt
	v_mul_f32_e32 v24, 0xbfb8aa3b, v24
	v_pk_mul_f32 v[26:27], v[20:21], v[86:87] op_sel_hi:[1,0]
	v_mul_f32_e32 v20, 0xbfb8aa3b, v22
	v_exp_f32_e32 v22, v20
	v_mul_f32_e32 v20, 0xbfb8aa3b, v23
	v_exp_f32_e32 v23, v20
	v_pk_mul_f32 v[20:21], v[18:19], v[86:87] op_sel_hi:[1,0]
	v_add_f32_e32 v18, 1.0, v22
	v_mul_f32_e32 v25, 0xbfb8aa3b, v25
	v_add_f32_e32 v19, 1.0, v23
	v_rcp_f32_e32 v18, v18
	v_rcp_f32_e32 v19, v19
	v_exp_f32_e32 v24, v24
	v_exp_f32_e32 v25, v25
	s_waitcnt vmcnt(8)
	v_lshlrev_b32_e32 v22, 16, v80
	v_and_b32_e32 v23, 0xffff0000, v80
	v_pk_fma_f32 v[18:19], v[18:19], v[22:23], v[76:77]
	v_add_f32_e32 v22, 1.0, v24
	v_add_f32_e32 v23, 1.0, v25
	v_rcp_f32_e32 v22, v22
	v_rcp_f32_e32 v23, v23
	v_mul_f32_e32 v20, 0xbfb8aa3b, v20
	v_lshlrev_b32_e32 v24, 16, v81
	v_and_b32_e32 v25, 0xffff0000, v81
	v_exp_f32_e32 v28, v20
	v_mul_f32_e32 v20, 0xbfb8aa3b, v21
	v_exp_f32_e32 v29, v20
	v_pk_fma_f32 v[20:21], v[22:23], v[24:25], v[78:79]
	v_mul_f32_e32 v25, 0xbfb8aa3b, v26
	v_exp_f32_e32 v26, v25
	v_mul_f32_e32 v25, 0xbfb8aa3b, v27
	v_exp_f32_e32 v27, v25
	v_add_f32_e32 v22, 1.0, v28
	v_add_f32_e32 v23, 1.0, v29
	v_rcp_f32_e32 v22, v22
	v_rcp_f32_e32 v23, v23
	v_add_f32_e32 v26, 1.0, v26
	v_add_f32_e32 v27, 1.0, v27
	v_rcp_f32_e32 v26, v26
	v_rcp_f32_e32 v27, v27
	v_lshlrev_b32_e32 v24, 16, v82
	v_and_b32_e32 v25, 0xffff0000, v82
	v_pk_fma_f32 v[22:23], v[22:23], v[24:25], v[72:73]
	v_lshlrev_b32_e32 v24, 16, v83
	v_and_b32_e32 v25, 0xffff0000, v83
	v_pk_mul_f32 v[14:15], v[14:15], v[58:59] op_sel_hi:[1,0]
	v_pk_fma_f32 v[24:25], v[26:27], v[24:25], v[74:75]
	global_store_dwordx4 v[60:61], v[18:21], off offset:512 nt
	global_store_dwordx4 v[60:61], v[22:25], off offset:528 nt
	v_pk_mul_f32 v[16:17], v[16:17], v[58:59] op_sel_hi:[1,0]
	v_pk_mul_f32 v[20:21], v[12:13], v[58:59] op_sel_hi:[1,0]
	v_mul_f32_e32 v12, 0xbfb8aa3b, v14
	v_exp_f32_e32 v14, v12
	v_mul_f32_e32 v12, 0xbfb8aa3b, v15
	v_exp_f32_e32 v15, v12
	v_pk_mul_f32 v[12:13], v[10:11], v[58:59] op_sel_hi:[1,0]
	v_add_f32_e32 v10, 1.0, v14
	v_mul_f32_e32 v16, 0xbfb8aa3b, v16
	v_add_f32_e32 v11, 1.0, v15
	v_mul_f32_e32 v17, 0xbfb8aa3b, v17
	v_rcp_f32_e32 v10, v10
	v_rcp_f32_e32 v11, v11
	v_exp_f32_e32 v16, v16
	v_exp_f32_e32 v17, v17
	s_waitcnt vmcnt(5)
	v_lshlrev_b32_e32 v14, 16, v50
	v_and_b32_e32 v15, 0xffff0000, v50
	v_pk_fma_f32 v[10:11], v[10:11], v[14:15], v[54:55]
	v_add_f32_e32 v14, 1.0, v16
	v_add_f32_e32 v15, 1.0, v17
	v_rcp_f32_e32 v14, v14
	v_rcp_f32_e32 v15, v15
	v_mul_f32_e32 v12, 0xbfb8aa3b, v12
	v_lshlrev_b32_e32 v16, 16, v51
	v_and_b32_e32 v17, 0xffff0000, v51
	v_exp_f32_e32 v22, v12
	v_mul_f32_e32 v12, 0xbfb8aa3b, v13
	v_exp_f32_e32 v23, v12
	v_pk_fma_f32 v[12:13], v[14:15], v[16:17], v[56:57]
	v_mul_f32_e32 v17, 0xbfb8aa3b, v20
	v_exp_f32_e32 v20, v17
	v_mul_f32_e32 v17, 0xbfb8aa3b, v21
	v_exp_f32_e32 v21, v17
	v_add_f32_e32 v14, 1.0, v22
	v_add_f32_e32 v15, 1.0, v23
	v_rcp_f32_e32 v14, v14
	v_rcp_f32_e32 v15, v15
	v_add_f32_e32 v20, 1.0, v20
	v_add_f32_e32 v21, 1.0, v21
	v_rcp_f32_e32 v20, v20
	v_rcp_f32_e32 v21, v21
	v_lshlrev_b64 v[18:19], 12, v[88:89]
	v_lshl_add_u64 v[18:19], s[22:23], 0, v[18:19]
	v_lshlrev_b32_e32 v16, 16, v52
	v_and_b32_e32 v17, 0xffff0000, v52
	v_pk_fma_f32 v[14:15], v[14:15], v[16:17], v[46:47]
	v_lshlrev_b32_e32 v16, 16, v53
	v_and_b32_e32 v17, 0xffff0000, v53
	v_lshl_add_u64 v[18:19], v[18:19], 0, v[122:123]
	v_pk_mul_f32 v[6:7], v[6:7], v[58:59] op_sel_hi:[1,0]
	v_pk_fma_f32 v[16:17], v[20:21], v[16:17], v[48:49]
	global_store_dwordx4 v[18:19], v[10:13], off nt
	global_store_dwordx4 v[18:19], v[14:17], off offset:16 nt
	v_pk_mul_f32 v[8:9], v[8:9], v[58:59] op_sel_hi:[1,0]
	v_pk_mul_f32 v[10:11], v[4:5], v[58:59] op_sel_hi:[1,0]
	v_mul_f32_e32 v4, 0xbfb8aa3b, v6
	v_exp_f32_e32 v6, v4
	v_mul_f32_e32 v4, 0xbfb8aa3b, v7
	v_exp_f32_e32 v7, v4
	v_pk_mul_f32 v[4:5], v[2:3], v[58:59] op_sel_hi:[1,0]
	v_add_f32_e32 v2, 1.0, v6
	v_mul_f32_e32 v8, 0xbfb8aa3b, v8
	v_add_f32_e32 v3, 1.0, v7
	v_mul_f32_e32 v9, 0xbfb8aa3b, v9
	v_rcp_f32_e32 v2, v2
	v_rcp_f32_e32 v3, v3
	v_exp_f32_e32 v8, v8
	v_exp_f32_e32 v9, v9
	s_waitcnt vmcnt(6)
	v_lshlrev_b32_e32 v6, 16, v38
	v_and_b32_e32 v7, 0xffff0000, v38
	v_pk_fma_f32 v[2:3], v[2:3], v[6:7], v[42:43]
	v_add_f32_e32 v6, 1.0, v8
	v_add_f32_e32 v7, 1.0, v9
	v_rcp_f32_e32 v6, v6
	v_rcp_f32_e32 v7, v7
	v_mul_f32_e32 v4, 0xbfb8aa3b, v4
	v_lshlrev_b32_e32 v8, 16, v39
	v_and_b32_e32 v9, 0xffff0000, v39
	v_exp_f32_e32 v12, v4
	v_mul_f32_e32 v4, 0xbfb8aa3b, v5
	v_exp_f32_e32 v13, v4
	v_pk_fma_f32 v[4:5], v[6:7], v[8:9], v[44:45]
	v_mul_f32_e32 v9, 0xbfb8aa3b, v10
	v_exp_f32_e32 v10, v9
	v_mul_f32_e32 v9, 0xbfb8aa3b, v11
	v_exp_f32_e32 v11, v9
	v_add_f32_e32 v6, 1.0, v12
	v_add_f32_e32 v7, 1.0, v13
	v_rcp_f32_e32 v6, v6
	v_rcp_f32_e32 v7, v7
	v_add_f32_e32 v10, 1.0, v10
	v_add_f32_e32 v11, 1.0, v11
	v_rcp_f32_e32 v10, v10
	v_rcp_f32_e32 v11, v11
	v_lshlrev_b32_e32 v8, 16, v40
	v_and_b32_e32 v9, 0xffff0000, v40
	v_pk_fma_f32 v[6:7], v[6:7], v[8:9], v[34:35]
	v_lshlrev_b32_e32 v8, 16, v41
	v_and_b32_e32 v9, 0xffff0000, v41
	v_pk_fma_f32 v[8:9], v[10:11], v[8:9], v[36:37]
	global_store_dwordx4 v[18:19], v[2:5], off offset:512 nt
	global_store_dwordx4 v[18:19], v[6:9], off offset:528 nt
	s_andn2_b64 vcc, exec, s[16:17]
	s_mov_b64 s[6:7], -1
	s_cbranch_vccnz .LBB0_1492
